# nt on the P0 weight-transpose (f32->bf16 WT) stores: streamed producer output, smaller dirty L2 footprint at the first seam
# speedup vs baseline: 1.0054x; 1.0026x over previous
; __global__ void __launch_bounds__(512, 2) fwd_mega(Args args) {
;     ...
;             const float* wp = w_ada + (size_t)(kpart * 64) * NMOD + 4 * cgp;
; #pragma unroll 4
;             for (int kk = 0; kk < 64; ++kk) { const f32x4 w = __builtin_nontemporal_load((const f32x4*)(wp + (size_t)kk * NMOD));
; #pragma unroll
;                 for (int v = 0; v < 5; ++v) acc[v] += w * sv[v * 64 + kk]; }
; #pragma unroll
;             for (int v = 0; v < 5; ++v) *(f32x4*)(part + (size_t)(kpart * 5 + v) * NMOD + 4 * cgp) = acc[v];
.LBB0_11:
	v_lshl_add_u64 v[38:39], v[26:27], 0, s[24:25]
	v_add_co_u32_e64 v40, s[0:1], s3, v38
	global_load_dwordx4 v[34:37], v[38:39], off nt
	s_nop 0
	v_addc_co_u32_e64 v41, s[0:1], 0, v39, s[0:1]
	v_add_co_u32_e64 v42, s[0:1], s6, v38
	v_mov_b32_e32 v33, s18
	s_nop 0
	v_addc_co_u32_e64 v43, s[0:1], 0, v39, s[0:1]
	v_add_co_u32_e64 v46, s[0:1], s7, v38
	s_add_u32 s24, s24, 0x30000
	s_nop 0
	v_addc_co_u32_e64 v47, s[0:1], 0, v39, s[0:1]
	global_load_dwordx4 v[38:41], v[40:41], off nt
	s_nop 0
	global_load_dwordx4 v[42:45], v[42:43], off nt
	s_nop 0
	global_load_dwordx4 v[46:49], v[46:47], off nt
	ds_read_b128 v[50:53], v33
	ds_read_b128 v[54:57], v33 offset:256
	ds_read_b128 v[58:61], v33 offset:512
	ds_read_b128 v[62:65], v33 offset:768
	ds_read_b128 v[66:69], v33 offset:1024
	s_addc_u32 s25, s25, 0
	s_add_i32 s18, s18, 16
	s_waitcnt lgkmcnt(4)
	v_mov_b32_e32 v70, v53
	s_waitcnt lgkmcnt(3)
	v_mov_b32_e32 v72, v57
	s_waitcnt lgkmcnt(2)
	v_mov_b32_e32 v74, v61
	s_waitcnt lgkmcnt(1)
	v_mov_b32_e32 v76, v65
	s_waitcnt lgkmcnt(0)
	v_mov_b32_e32 v78, v69
	s_cmp_eq_u32 s24, 0x300000
	s_waitcnt vmcnt(3)
	v_pk_fma_f32 v[20:21], v[36:37], v[50:51], v[20:21] op_sel_hi:[1,0,1]
	v_pk_fma_f32 v[18:19], v[34:35], v[50:51], v[18:19] op_sel_hi:[1,0,1]
	v_pk_fma_f32 v[16:17], v[36:37], v[54:55], v[16:17] op_sel_hi:[1,0,1]
	v_pk_fma_f32 v[14:15], v[34:35], v[54:55], v[14:15] op_sel_hi:[1,0,1]
	v_pk_fma_f32 v[12:13], v[36:37], v[58:59], v[12:13] op_sel_hi:[1,0,1]
	v_pk_fma_f32 v[10:11], v[34:35], v[58:59], v[10:11] op_sel_hi:[1,0,1]
	v_pk_fma_f32 v[8:9], v[36:37], v[62:63], v[8:9] op_sel_hi:[1,0,1]
	v_pk_fma_f32 v[6:7], v[34:35], v[62:63], v[6:7] op_sel_hi:[1,0,1]
	v_pk_fma_f32 v[4:5], v[36:37], v[66:67], v[4:5] op_sel_hi:[1,0,1]
	v_pk_fma_f32 v[2:3], v[34:35], v[66:67], v[2:3] op_sel_hi:[1,0,1]
	s_waitcnt vmcnt(2)
	v_pk_fma_f32 v[18:19], v[38:39], v[50:51], v[18:19] op_sel:[0,1,0]
	v_pk_fma_f32 v[20:21], v[40:41], v[50:51], v[20:21] op_sel:[0,1,0]
	v_pk_fma_f32 v[14:15], v[38:39], v[54:55], v[14:15] op_sel:[0,1,0]
	v_pk_fma_f32 v[16:17], v[40:41], v[54:55], v[16:17] op_sel:[0,1,0]
	v_pk_fma_f32 v[10:11], v[38:39], v[58:59], v[10:11] op_sel:[0,1,0]
	v_pk_fma_f32 v[12:13], v[40:41], v[58:59], v[12:13] op_sel:[0,1,0]
	v_pk_fma_f32 v[6:7], v[38:39], v[62:63], v[6:7] op_sel:[0,1,0]
	v_pk_fma_f32 v[8:9], v[40:41], v[62:63], v[8:9] op_sel:[0,1,0]
	v_pk_fma_f32 v[2:3], v[38:39], v[66:67], v[2:3] op_sel:[0,1,0]
	v_pk_fma_f32 v[4:5], v[40:41], v[66:67], v[4:5] op_sel:[0,1,0]
	s_waitcnt vmcnt(1)
	v_pk_fma_f32 v[20:21], v[44:45], v[52:53], v[20:21] op_sel_hi:[1,0,1]
	v_pk_fma_f32 v[18:19], v[42:43], v[52:53], v[18:19] op_sel_hi:[1,0,1]
	v_pk_fma_f32 v[16:17], v[44:45], v[56:57], v[16:17] op_sel_hi:[1,0,1]
	v_pk_fma_f32 v[14:15], v[42:43], v[56:57], v[14:15] op_sel_hi:[1,0,1]
	v_pk_fma_f32 v[12:13], v[44:45], v[60:61], v[12:13] op_sel_hi:[1,0,1]
	v_pk_fma_f32 v[10:11], v[42:43], v[60:61], v[10:11] op_sel_hi:[1,0,1]
	v_pk_fma_f32 v[8:9], v[44:45], v[64:65], v[8:9] op_sel_hi:[1,0,1]
	v_pk_fma_f32 v[6:7], v[42:43], v[64:65], v[6:7] op_sel_hi:[1,0,1]
	v_pk_fma_f32 v[4:5], v[44:45], v[68:69], v[4:5] op_sel_hi:[1,0,1]
	v_pk_fma_f32 v[2:3], v[42:43], v[68:69], v[2:3] op_sel_hi:[1,0,1]
	s_waitcnt vmcnt(0)
	v_pk_fma_f32 v[20:21], v[48:49], v[70:71], v[20:21] op_sel_hi:[1,0,1]
	v_pk_fma_f32 v[18:19], v[46:47], v[70:71], v[18:19] op_sel_hi:[1,0,1]
	v_pk_fma_f32 v[16:17], v[48:49], v[72:73], v[16:17] op_sel_hi:[1,0,1]
	v_pk_fma_f32 v[14:15], v[46:47], v[72:73], v[14:15] op_sel_hi:[1,0,1]
	v_pk_fma_f32 v[12:13], v[48:49], v[74:75], v[12:13] op_sel_hi:[1,0,1]
	v_pk_fma_f32 v[10:11], v[46:47], v[74:75], v[10:11] op_sel_hi:[1,0,1]
	v_pk_fma_f32 v[8:9], v[48:49], v[76:77], v[8:9] op_sel_hi:[1,0,1]
	v_pk_fma_f32 v[6:7], v[46:47], v[76:77], v[6:7] op_sel_hi:[1,0,1]
	v_pk_fma_f32 v[4:5], v[48:49], v[78:79], v[4:5] op_sel_hi:[1,0,1]
	v_pk_fma_f32 v[2:3], v[46:47], v[78:79], v[2:3] op_sel_hi:[1,0,1]
	s_cbranch_scc0 .LBB0_11
	s_mul_i32 s17, s17, 5
	v_lshl_add_u64 v[24:25], v[24:25], 2, s[22:23]
	v_mad_i64_i32 v[26:27], s[0:1], s17, v32, v[24:25]
	s_add_i32 s0, s17, 1
	global_store_dwordx4 v[26:27], v[18:21], off nt
	s_add_i32 s16, s16, s42
	s_nop 0
	v_mad_i64_i32 v[18:19], s[0:1], s0, v32, v[24:25]
	s_add_i32 s0, s17, 2
	global_store_dwordx4 v[18:19], v[14:17], off nt
	s_nop 1
	v_mad_i64_i32 v[14:15], s[0:1], s0, v32, v[24:25]
	s_add_i32 s0, s17, 3
	global_store_dwordx4 v[14:15], v[10:13], off nt
	s_add_i32 s17, s17, 4
	s_cmpk_gt_i32 s16, 0xbf
	v_mad_i64_i32 v[10:11], s[0:1], s0, v32, v[24:25]
	global_store_dwordx4 v[10:11], v[6:9], off nt
	s_nop 1
	v_mad_i64_i32 v[6:7], s[0:1], s17, v32, v[24:25]
	global_store_dwordx4 v[6:7], v[2:5], off nt
	s_barrier
	s_cbranch_scc0 .LBB0_8

; #define LAS __attribute__((address_space(3)))
; DI unsigned pk2(float lo, float hi) { f32x2_t v = {lo, hi}; bf16x2_t b = __builtin_convertvector(v, bf16x2_t); return __builtin_bit_cast(unsigned, b); }
; DI void transpose_item(const float* W, int K, int N, bf16* WT, int k0, int n0, int drow0, LAS float* scr, int lane) {
; #pragma unroll 8
;     for (int i = 0; i < 32; ++i) { const int kk = 2 * i + (lane >> 5); scr[kk * 33 + (lane & 31)] = __builtin_nontemporal_load(W + (size_t)(k0 + kk) * N + n0 + (lane & 31)); }
;     asm volatile("s_waitcnt lgkmcnt(0)" ::: "memory");
;     const int c = lane & 7;
; #pragma unroll
;     for (int j = 0; j < 4; ++j) { const int n = (lane >> 3) + 8 * j; const LAS float* s = scr + (8 * c) * 33 + n;
;         u32x4 o; o.x = pk2(s[0 * 33], s[1 * 33]); o.y = pk2(s[2 * 33], s[3 * 33]); o.z = pk2(s[4 * 33], s[5 * 33]); o.w = pk2(s[6 * 33], s[7 * 33]);
;         *(u32x4*)(WT + (size_t)(drow0 + n) * K + k0 + 8 * c) = o; }
;     asm volatile("s_waitcnt lgkmcnt(0)" ::: "memory");
; __global__ void __launch_bounds__(512, 2) fwd_mega(Args args) {
;     ...
;             { const int kb = r / 64, nb = r % 64; transpose_item(w_f2, FFH, DM, Wf2t, 64 * kb, 32 * nb, 32 * nb, scr, lane); }
.LBB0_22:
	v_add_u32_e32 v35, s0, v32
	v_add_u32_e32 v34, 0xffff9400, v35
	v_add_u32_e32 v36, 0xffff9402, v35
	v_add_u32_e32 v38, 0xffff9404, v35
	v_add_u32_e32 v40, 0xffff9406, v35
	v_add_u32_e32 v42, 0xffff9408, v35
	v_add_u32_e32 v44, 0xffff940a, v35
	v_add_u32_e32 v84, 0xffff940c, v35
	v_add_u32_e32 v86, 0xffff940e, v35
	v_ashrrev_i32_e32 v35, 31, v34
	v_ashrrev_i32_e32 v37, 31, v36
	v_ashrrev_i32_e32 v39, 31, v38
	v_ashrrev_i32_e32 v41, 31, v40
	v_ashrrev_i32_e32 v43, 31, v42
	v_ashrrev_i32_e32 v45, 31, v44
	v_ashrrev_i32_e32 v85, 31, v84
	v_ashrrev_i32_e32 v87, 31, v86
	v_lshlrev_b64 v[34:35], 13, v[34:35]
	v_lshlrev_b64 v[36:37], 13, v[36:37]
	v_lshlrev_b64 v[38:39], 13, v[38:39]
	v_lshlrev_b64 v[40:41], 13, v[40:41]
	v_lshlrev_b64 v[42:43], 13, v[42:43]
	v_lshlrev_b64 v[44:45], 13, v[44:45]
	v_lshlrev_b64 v[84:85], 13, v[84:85]
	v_lshlrev_b64 v[86:87], 13, v[86:87]
	v_lshl_add_u64 v[34:35], v[30:31], 0, v[34:35]
	v_lshl_add_u64 v[36:37], v[30:31], 0, v[36:37]
	v_lshl_add_u64 v[38:39], v[30:31], 0, v[38:39]
	v_lshl_add_u64 v[40:41], v[30:31], 0, v[40:41]
	v_lshl_add_u64 v[42:43], v[30:31], 0, v[42:43]
	v_lshl_add_u64 v[44:45], v[30:31], 0, v[44:45]
	v_lshl_add_u64 v[84:85], v[30:31], 0, v[84:85]
	v_lshl_add_u64 v[86:87], v[30:31], 0, v[86:87]
	global_load_dword v34, v[34:35], off nt
	s_nop 0
	global_load_dword v35, v[36:37], off nt
	s_nop 0
	global_load_dword v36, v[38:39], off nt
	global_load_dword v37, v[40:41], off nt
	s_nop 0
	global_load_dword v38, v[42:43], off nt
	global_load_dword v39, v[44:45], off nt
	global_load_dword v40, v[84:85], off nt
	global_load_dword v41, v[86:87], off nt
	s_add_i32 s0, s0, 16
	v_add_u32_e32 v42, 0x400, v33
	s_cmp_lg_u32 s0, 64
	s_waitcnt vmcnt(6)
	ds_write2_b32 v33, v34, v35 offset1:66
	s_waitcnt vmcnt(4)
	ds_write2_b32 v33, v36, v37 offset0:132 offset1:198
	s_waitcnt vmcnt(2)
	ds_write2_b32 v42, v38, v39 offset0:8 offset1:74
	s_waitcnt vmcnt(0)
	ds_write2_b32 v42, v40, v41 offset0:140 offset1:206
	v_add_u32_e32 v33, 0x840, v33
	s_cbranch_scc1 .LBB0_22
	s_waitcnt lgkmcnt(0)
	v_add_u32_e32 v83, 0x1000, v47
	ds_read2_b32 v[34:35], v83 offset0:33 offset1:41
	ds_read2_b32 v[36:37], v83 offset1:8
	ds_read2_b32 v[38:39], v83 offset0:66 offset1:74
	ds_read2_b32 v[40:41], v83 offset0:99 offset1:107
	ds_read2_b32 v[42:43], v83 offset0:132 offset1:140
	ds_read2_b32 v[44:45], v83 offset0:165 offset1:173
	ds_read2_b32 v[84:85], v83 offset0:198 offset1:206
	ds_read2_b32 v[86:87], v83 offset0:231 offset1:239
	s_and_b32 s0, s18, 0x7fffffc0
	s_addk_i32 s0, 0x9400
	v_lshl_add_u64 v[88:89], s[0:1], 1, v[6:7]
	s_waitcnt lgkmcnt(6)
	v_cvt_pk_bf16_f32 v30, v36, v34
	v_add_u32_e32 v34, s8, v46
	s_waitcnt lgkmcnt(4)
	v_cvt_pk_bf16_f32 v31, v38, v40
	s_waitcnt lgkmcnt(2)
	v_cvt_pk_bf16_f32 v32, v42, v44
	s_waitcnt lgkmcnt(0)
	v_cvt_pk_bf16_f32 v33, v84, v86
	v_mad_i64_i32 v[90:91], s[22:23], v34, s16, v[88:89]
	global_store_dwordx4 v[90:91], v[30:33], off nt
	v_add_u32_e32 v34, s8, v48
	s_nop 0
	v_cvt_pk_bf16_f32 v30, v37, v35
	v_cvt_pk_bf16_f32 v31, v39, v41
	v_cvt_pk_bf16_f32 v32, v43, v45
	v_cvt_pk_bf16_f32 v33, v85, v87
	ds_read2_b32 v[36:37], v83 offset0:49 offset1:57
	ds_read2_b32 v[38:39], v83 offset0:16 offset1:24
	ds_read2_b32 v[40:41], v83 offset0:82 offset1:90
	ds_read2_b32 v[42:43], v83 offset0:115 offset1:123
	ds_read2_b32 v[44:45], v83 offset0:148 offset1:156
	ds_read2_b32 v[84:85], v83 offset0:181 offset1:189
	ds_read2_b32 v[86:87], v83 offset0:214 offset1:222
	ds_read2_b32 v[90:91], v83 offset0:247 offset1:255
	v_mad_i64_i32 v[34:35], s[22:23], v34, s16, v[88:89]
	global_store_dwordx4 v[34:35], v[30:33], off nt
	v_add_u32_e32 v34, s8, v49
	v_mad_i64_i32 v[34:35], s[22:23], v34, s16, v[88:89]
	s_waitcnt lgkmcnt(6)
	v_cvt_pk_bf16_f32 v30, v38, v36
	s_waitcnt lgkmcnt(4)
	v_cvt_pk_bf16_f32 v31, v40, v42
	s_waitcnt lgkmcnt(2)
	v_cvt_pk_bf16_f32 v32, v44, v84
	s_waitcnt lgkmcnt(0)
	v_cvt_pk_bf16_f32 v33, v86, v90
	global_store_dwordx4 v[34:35], v[30:33], off nt
	v_add_u32_e32 v34, s8, v50
	v_mad_i64_i32 v[34:35], s[8:9], v34, s16, v[88:89]
	v_cvt_pk_bf16_f32 v30, v39, v37
	v_cvt_pk_bf16_f32 v31, v41, v43
	v_cvt_pk_bf16_f32 v32, v45, v85
	v_cvt_pk_bf16_f32 v33, v87, v91
	global_store_dwordx4 v[34:35], v[30:33], off nt
	s_waitcnt lgkmcnt(0)
	s_mov_b64 s[8:9], 0

; #define LAS __attribute__((address_space(3)))
; DI unsigned pk2(float lo, float hi) { f32x2_t v = {lo, hi}; bf16x2_t b = __builtin_convertvector(v, bf16x2_t); return __builtin_bit_cast(unsigned, b); }
; DI void transpose_item(const float* W, int K, int N, bf16* WT, int k0, int n0, int drow0, LAS float* scr, int lane) {
; #pragma unroll 8
;     for (int i = 0; i < 32; ++i) { const int kk = 2 * i + (lane >> 5); scr[kk * 33 + (lane & 31)] = __builtin_nontemporal_load(W + (size_t)(k0 + kk) * N + n0 + (lane & 31)); }
;     asm volatile("s_waitcnt lgkmcnt(0)" ::: "memory");
;     const int c = lane & 7;
; #pragma unroll
;     for (int j = 0; j < 4; ++j) { const int n = (lane >> 3) + 8 * j; const LAS float* s = scr + (8 * c) * 33 + n;
;         u32x4 o; o.x = pk2(s[0 * 33], s[1 * 33]); o.y = pk2(s[2 * 33], s[3 * 33]); o.z = pk2(s[4 * 33], s[5 * 33]); o.w = pk2(s[6 * 33], s[7 * 33]);
;         *(u32x4*)(WT + (size_t)(drow0 + n) * K + k0 + 8 * c) = o; }
;     asm volatile("s_waitcnt lgkmcnt(0)" ::: "memory");
; __global__ void __launch_bounds__(512, 2) fwd_mega(Args args) {
;     ...
;             if (r < I_F1) { const int kb = r / 352, nb = r % 352, n0 = 32 * nb; const int isu = n0 >= FFH, j = n0 - isu * FFH;
;                 transpose_item(w_f1, DM, 2 * FFH, Wf1t, 64 * kb, n0, (j >> 7) * 256 + isu * 128 + (j & 127), scr, lane); continue; } r -= I_F1;
.LBB0_26:
	v_lshl_add_u64 v[84:85], v[44:45], 0, s[8:9]
	v_lshl_add_u64 v[86:87], v[42:43], 0, s[8:9]
	v_lshl_add_u64 v[88:89], v[40:41], 0, s[8:9]
	v_lshl_add_u64 v[90:91], v[38:39], 0, s[8:9]
	v_lshl_add_u64 v[92:93], v[36:37], 0, s[8:9]
	v_lshl_add_u64 v[94:95], v[34:35], 0, s[8:9]
	v_lshl_add_u64 v[96:97], v[32:33], 0, s[8:9]
	v_lshl_add_u64 v[98:99], v[30:31], 0, s[8:9]
	global_load_dword v84, v[84:85], off nt
	s_nop 0
	global_load_dword v85, v[86:87], off nt
	s_nop 0
	global_load_dword v86, v[88:89], off nt
	global_load_dword v87, v[90:91], off nt
	s_nop 0
	global_load_dword v88, v[92:93], off nt
	global_load_dword v89, v[94:95], off nt
	global_load_dword v90, v[96:97], off nt
	global_load_dword v91, v[98:99], off nt
	s_add_u32 s8, s8, 0xb0000
	s_addc_u32 s9, s9, 0
	v_add_u32_e32 v92, 0x400, v83
	s_cmp_lg_u32 s8, 0x2c0000
	s_waitcnt vmcnt(6)
	ds_write2_b32 v83, v84, v85 offset1:66
	s_waitcnt vmcnt(4)
	ds_write2_b32 v83, v86, v87 offset0:132 offset1:198
	s_waitcnt vmcnt(2)
	ds_write2_b32 v92, v88, v89 offset0:8 offset1:74
	s_waitcnt vmcnt(0)
	ds_write2_b32 v92, v90, v91 offset0:140 offset1:206
	v_add_u32_e32 v83, 0x840, v83
	s_cbranch_scc1 .LBB0_26
	s_and_b32 s0, 0xffff, s23
	s_and_b32 s8, 0xffff, s22
	s_cmpk_gt_u32 s8, 0xaf
	s_cselect_b32 s8, 0xffffea00, 0
	s_cselect_b32 s9, 0x80, 0
	s_add_i32 s8, s8, s0
	s_lshl_b32 s8, s8, 1
	s_and_b32 s0, s0, 0x60
	s_waitcnt lgkmcnt(0)
	v_add_u32_e32 v83, 0x1000, v47
	s_or_b32 s0, s0, s9
	s_and_b32 s8, s8, 0xffffff00
	ds_read2_b32 v[34:35], v83 offset0:33 offset1:41
	ds_read2_b32 v[36:37], v83 offset1:8
	ds_read2_b32 v[38:39], v83 offset0:66 offset1:74
	ds_read2_b32 v[40:41], v83 offset0:99 offset1:107
	ds_read2_b32 v[42:43], v83 offset0:132 offset1:140
	ds_read2_b32 v[44:45], v83 offset0:165 offset1:173
	ds_read2_b32 v[84:85], v83 offset0:198 offset1:206
	ds_read2_b32 v[86:87], v83 offset0:231 offset1:239
	s_or_b32 s8, s0, s8
	s_and_b32 s0, 0xffff, s21
	v_add_u32_e32 v90, s8, v46
	s_lshl_b32 s0, s0, 1
	v_ashrrev_i32_e32 v91, 31, v90
	v_lshl_add_u64 v[88:89], v[8:9], 0, s[0:1]
	v_lshlrev_b64 v[90:91], 12, v[90:91]
	s_waitcnt lgkmcnt(6)
	v_cvt_pk_bf16_f32 v30, v36, v34
	s_waitcnt lgkmcnt(4)
	v_cvt_pk_bf16_f32 v31, v38, v40
	s_waitcnt lgkmcnt(2)
	v_cvt_pk_bf16_f32 v32, v42, v44
	s_waitcnt lgkmcnt(0)
	v_cvt_pk_bf16_f32 v33, v84, v86
	v_lshl_add_u64 v[90:91], v[88:89], 0, v[90:91]
	v_add_u32_e32 v34, s8, v48
	global_store_dwordx4 v[90:91], v[30:33], off nt
	s_nop 1
	v_cvt_pk_bf16_f32 v30, v37, v35
	v_ashrrev_i32_e32 v35, 31, v34
	v_cvt_pk_bf16_f32 v31, v39, v41
	v_cvt_pk_bf16_f32 v32, v43, v45
	v_cvt_pk_bf16_f32 v33, v85, v87
	v_lshlrev_b64 v[34:35], 12, v[34:35]
	ds_read2_b32 v[36:37], v83 offset0:49 offset1:57
	ds_read2_b32 v[38:39], v83 offset0:16 offset1:24
	ds_read2_b32 v[40:41], v83 offset0:82 offset1:90
	ds_read2_b32 v[42:43], v83 offset0:115 offset1:123
	ds_read2_b32 v[44:45], v83 offset0:148 offset1:156
	ds_read2_b32 v[84:85], v83 offset0:181 offset1:189
	ds_read2_b32 v[86:87], v83 offset0:214 offset1:222
	ds_read2_b32 v[90:91], v83 offset0:247 offset1:255
	v_lshl_add_u64 v[34:35], v[88:89], 0, v[34:35]
	global_store_dwordx4 v[34:35], v[30:33], off nt
	v_add_u32_e32 v34, s8, v49
	v_ashrrev_i32_e32 v35, 31, v34
	v_lshlrev_b64 v[34:35], 12, v[34:35]
	s_waitcnt lgkmcnt(6)
	v_cvt_pk_bf16_f32 v30, v38, v36
	s_waitcnt lgkmcnt(4)
	v_cvt_pk_bf16_f32 v31, v40, v42
	s_waitcnt lgkmcnt(2)
	v_cvt_pk_bf16_f32 v32, v44, v84
	s_waitcnt lgkmcnt(0)
	v_cvt_pk_bf16_f32 v33, v86, v90
	v_lshl_add_u64 v[34:35], v[88:89], 0, v[34:35]
	global_store_dwordx4 v[34:35], v[30:33], off nt
	v_add_u32_e32 v34, s8, v50
	v_ashrrev_i32_e32 v35, 31, v34
	v_lshlrev_b64 v[34:35], 12, v[34:35]
	v_cvt_pk_bf16_f32 v30, v39, v37
	v_cvt_pk_bf16_f32 v31, v41, v43
	v_cvt_pk_bf16_f32 v32, v45, v85
	v_cvt_pk_bf16_f32 v33, v87, v91
	v_lshl_add_u64 v[34:35], v[88:89], 0, v[34:35]
	global_store_dwordx4 v[34:35], v[30:33], off nt
	s_waitcnt lgkmcnt(0)

; #define LAS __attribute__((address_space(3)))
; DI unsigned pk2(float lo, float hi) { f32x2_t v = {lo, hi}; bf16x2_t b = __builtin_convertvector(v, bf16x2_t); return __builtin_bit_cast(unsigned, b); }
; DI void transpose_item(const float* W, int K, int N, bf16* WT, int k0, int n0, int drow0, LAS float* scr, int lane) {
; #pragma unroll 8
;     for (int i = 0; i < 32; ++i) { const int kk = 2 * i + (lane >> 5); scr[kk * 33 + (lane & 31)] = __builtin_nontemporal_load(W + (size_t)(k0 + kk) * N + n0 + (lane & 31)); }
;     asm volatile("s_waitcnt lgkmcnt(0)" ::: "memory");
;     const int c = lane & 7;
; #pragma unroll
;     for (int j = 0; j < 4; ++j) { const int n = (lane >> 3) + 8 * j; const LAS float* s = scr + (8 * c) * 33 + n;
;         u32x4 o; o.x = pk2(s[0 * 33], s[1 * 33]); o.y = pk2(s[2 * 33], s[3 * 33]); o.z = pk2(s[4 * 33], s[5 * 33]); o.w = pk2(s[6 * 33], s[7 * 33]);
;         *(u32x4*)(WT + (size_t)(drow0 + n) * K + k0 + 8 * c) = o; }
;     asm volatile("s_waitcnt lgkmcnt(0)" ::: "memory");
; __global__ void __launch_bounds__(512, 2) fwd_mega(Args args) {
;     ...
;             if (r < I_OUT) { const int kb = r / 64, nb = r % 64; transpose_item(w_out, DM, DM, Woutt, 64 * kb, 32 * nb, 32 * nb, scr, lane); continue; } r -= I_OUT;
.LBB0_31:
	v_lshl_add_u64 v[84:85], v[44:45], 0, s[8:9]
	v_lshl_add_u64 v[86:87], v[42:43], 0, s[8:9]
	v_lshl_add_u64 v[88:89], v[40:41], 0, s[8:9]
	v_lshl_add_u64 v[90:91], v[38:39], 0, s[8:9]
	v_lshl_add_u64 v[92:93], v[36:37], 0, s[8:9]
	v_lshl_add_u64 v[94:95], v[34:35], 0, s[8:9]
	v_lshl_add_u64 v[96:97], v[32:33], 0, s[8:9]
	v_lshl_add_u64 v[98:99], v[30:31], 0, s[8:9]
	global_load_dword v84, v[84:85], off nt
	s_nop 0
	global_load_dword v85, v[86:87], off nt
	s_nop 0
	global_load_dword v86, v[88:89], off nt
	global_load_dword v87, v[90:91], off nt
	s_nop 0
	global_load_dword v88, v[92:93], off nt
	global_load_dword v89, v[94:95], off nt
	global_load_dword v90, v[96:97], off nt
	global_load_dword v91, v[98:99], off nt
	s_add_u32 s8, s8, 0x20000
	s_addc_u32 s9, s9, 0
	v_add_u32_e32 v92, 0x400, v83
	s_cmp_lg_u32 s8, 0x80000
	s_waitcnt vmcnt(6)
	ds_write2_b32 v83, v84, v85 offset1:66
	s_waitcnt vmcnt(4)
	ds_write2_b32 v83, v86, v87 offset0:132 offset1:198
	s_waitcnt vmcnt(2)
	ds_write2_b32 v92, v88, v89 offset0:8 offset1:74
	s_waitcnt vmcnt(0)
	ds_write2_b32 v92, v90, v91 offset0:140 offset1:206
	v_add_u32_e32 v83, 0x840, v83
	s_cbranch_scc1 .LBB0_31
	s_waitcnt lgkmcnt(0)
	v_add_u32_e32 v83, 0x1000, v47
	s_lshl_b32 s8, s18, 5
	ds_read2_b32 v[34:35], v83 offset0:33 offset1:41
	ds_read2_b32 v[36:37], v83 offset1:8
	ds_read2_b32 v[38:39], v83 offset0:66 offset1:74
	ds_read2_b32 v[40:41], v83 offset0:99 offset1:107
	ds_read2_b32 v[42:43], v83 offset0:132 offset1:140
	ds_read2_b32 v[44:45], v83 offset0:165 offset1:173
	ds_read2_b32 v[84:85], v83 offset0:198 offset1:206
	ds_read2_b32 v[86:87], v83 offset0:231 offset1:239
	s_and_b32 s8, s8, 0x7e0
	v_add_u32_e32 v90, s8, v46
	s_add_i32 s0, s19, 0xffffc800
	v_ashrrev_i32_e32 v91, 31, v90
	v_lshl_add_u64 v[88:89], s[0:1], 1, v[10:11]
	v_lshlrev_b64 v[90:91], 12, v[90:91]
	s_waitcnt lgkmcnt(6)
	v_cvt_pk_bf16_f32 v30, v36, v34
	s_waitcnt lgkmcnt(4)
	v_cvt_pk_bf16_f32 v31, v38, v40
	s_waitcnt lgkmcnt(2)
	v_cvt_pk_bf16_f32 v32, v42, v44
	s_waitcnt lgkmcnt(0)
	v_cvt_pk_bf16_f32 v33, v84, v86
	v_lshl_add_u64 v[90:91], v[88:89], 0, v[90:91]
	v_add_u32_e32 v34, s8, v48
	global_store_dwordx4 v[90:91], v[30:33], off nt
	s_nop 1
	v_cvt_pk_bf16_f32 v30, v37, v35
	v_ashrrev_i32_e32 v35, 31, v34
	v_cvt_pk_bf16_f32 v31, v39, v41
	v_cvt_pk_bf16_f32 v32, v43, v45
	v_cvt_pk_bf16_f32 v33, v85, v87
	v_lshlrev_b64 v[34:35], 12, v[34:35]
	ds_read2_b32 v[36:37], v83 offset0:49 offset1:57
	ds_read2_b32 v[38:39], v83 offset0:16 offset1:24
	ds_read2_b32 v[40:41], v83 offset0:82 offset1:90
	ds_read2_b32 v[42:43], v83 offset0:115 offset1:123
	ds_read2_b32 v[44:45], v83 offset0:148 offset1:156
	ds_read2_b32 v[84:85], v83 offset0:181 offset1:189
	ds_read2_b32 v[86:87], v83 offset0:214 offset1:222
	ds_read2_b32 v[90:91], v83 offset0:247 offset1:255
	v_lshl_add_u64 v[34:35], v[88:89], 0, v[34:35]
	global_store_dwordx4 v[34:35], v[30:33], off nt
	v_add_u32_e32 v34, s8, v49
	v_ashrrev_i32_e32 v35, 31, v34
	v_lshlrev_b64 v[34:35], 12, v[34:35]
	s_waitcnt lgkmcnt(6)
	v_cvt_pk_bf16_f32 v30, v38, v36
	s_waitcnt lgkmcnt(4)
	v_cvt_pk_bf16_f32 v31, v40, v42
	s_waitcnt lgkmcnt(2)
	v_cvt_pk_bf16_f32 v32, v44, v84
	s_waitcnt lgkmcnt(0)
	v_cvt_pk_bf16_f32 v33, v86, v90
	v_lshl_add_u64 v[34:35], v[88:89], 0, v[34:35]
	global_store_dwordx4 v[34:35], v[30:33], off nt
	v_add_u32_e32 v34, s8, v50
	v_ashrrev_i32_e32 v35, 31, v34
	v_lshlrev_b64 v[34:35], 12, v[34:35]
	v_cvt_pk_bf16_f32 v30, v39, v37
	v_cvt_pk_bf16_f32 v31, v41, v43
	v_cvt_pk_bf16_f32 v32, v45, v85
	v_cvt_pk_bf16_f32 v33, v87, v91
	v_lshl_add_u64 v[34:35], v[88:89], 0, v[34:35]
	global_store_dwordx4 v[34:35], v[30:33], off nt
	s_waitcnt lgkmcnt(0)

; #define LAS __attribute__((address_space(3)))
; DI unsigned pk2(float lo, float hi) { f32x2_t v = {lo, hi}; bf16x2_t b = __builtin_convertvector(v, bf16x2_t); return __builtin_bit_cast(unsigned, b); }
; DI void transpose_item(const float* W, int K, int N, bf16* WT, int k0, int n0, int drow0, LAS float* scr, int lane) {
; #pragma unroll 8
;     for (int i = 0; i < 32; ++i) { const int kk = 2 * i + (lane >> 5); scr[kk * 33 + (lane & 31)] = __builtin_nontemporal_load(W + (size_t)(k0 + kk) * N + n0 + (lane & 31)); }
;     asm volatile("s_waitcnt lgkmcnt(0)" ::: "memory");
;     const int c = lane & 7;
; #pragma unroll
;     for (int j = 0; j < 4; ++j) { const int n = (lane >> 3) + 8 * j; const LAS float* s = scr + (8 * c) * 33 + n;
;         u32x4 o; o.x = pk2(s[0 * 33], s[1 * 33]); o.y = pk2(s[2 * 33], s[3 * 33]); o.z = pk2(s[4 * 33], s[5 * 33]); o.w = pk2(s[6 * 33], s[7 * 33]);
;         *(u32x4*)(WT + (size_t)(drow0 + n) * K + k0 + 8 * c) = o; }
;     asm volatile("s_waitcnt lgkmcnt(0)" ::: "memory");
; __global__ void __launch_bounds__(512, 2) fwd_mega(Args args) {
;     ...
;             if (r < I_PA) { const int kb = r / 64, nb = r % 64; transpose_item(w_pb, 1024, DM, Wpbt, 64 * kb, 32 * nb, 32 * nb, scr, lane); continue; } r -= I_PA;
.LBB0_36:
	v_lshl_add_u64 v[84:85], v[44:45], 0, s[8:9]
	v_lshl_add_u64 v[86:87], v[42:43], 0, s[8:9]
	v_lshl_add_u64 v[88:89], v[40:41], 0, s[8:9]
	v_lshl_add_u64 v[90:91], v[38:39], 0, s[8:9]
	v_lshl_add_u64 v[92:93], v[36:37], 0, s[8:9]
	v_lshl_add_u64 v[94:95], v[34:35], 0, s[8:9]
	v_lshl_add_u64 v[96:97], v[32:33], 0, s[8:9]
	v_lshl_add_u64 v[98:99], v[30:31], 0, s[8:9]
	global_load_dword v84, v[84:85], off nt
	s_nop 0
	global_load_dword v85, v[86:87], off nt
	s_nop 0
	global_load_dword v86, v[88:89], off nt
	global_load_dword v87, v[90:91], off nt
	s_nop 0
	global_load_dword v88, v[92:93], off nt
	global_load_dword v89, v[94:95], off nt
	global_load_dword v90, v[96:97], off nt
	global_load_dword v91, v[98:99], off nt
	s_add_u32 s8, s8, 0x20000
	s_addc_u32 s9, s9, 0
	v_add_u32_e32 v92, 0x400, v83
	s_cmp_lg_u32 s8, 0x80000
	s_waitcnt vmcnt(6)
	ds_write2_b32 v83, v84, v85 offset1:66
	s_waitcnt vmcnt(4)
	ds_write2_b32 v83, v86, v87 offset0:132 offset1:198
	s_waitcnt vmcnt(2)
	ds_write2_b32 v92, v88, v89 offset0:8 offset1:74
	s_waitcnt vmcnt(0)
	ds_write2_b32 v92, v90, v91 offset0:140 offset1:206
	v_add_u32_e32 v83, 0x840, v83
	s_cbranch_scc1 .LBB0_36
	s_waitcnt lgkmcnt(0)
	v_add_u32_e32 v83, 0x1000, v47
	s_lshl_b32 s8, s18, 5
	ds_read2_b32 v[34:35], v83 offset0:33 offset1:41
	ds_read2_b32 v[36:37], v83 offset1:8
	ds_read2_b32 v[38:39], v83 offset0:66 offset1:74
	ds_read2_b32 v[40:41], v83 offset0:99 offset1:107
	ds_read2_b32 v[42:43], v83 offset0:132 offset1:140
	ds_read2_b32 v[44:45], v83 offset0:165 offset1:173
	ds_read2_b32 v[84:85], v83 offset0:198 offset1:206
	ds_read2_b32 v[86:87], v83 offset0:231 offset1:239
	s_and_b32 s8, s8, 0x7e0
	v_add_u32_e32 v90, s8, v46
	s_add_i32 s0, s19, 0xffffcc00
	v_ashrrev_i32_e32 v91, 31, v90
	v_lshl_add_u64 v[88:89], s[0:1], 1, v[12:13]
	v_lshlrev_b64 v[90:91], 11, v[90:91]
	s_waitcnt lgkmcnt(6)
	v_cvt_pk_bf16_f32 v30, v36, v34
	s_waitcnt lgkmcnt(4)
	v_cvt_pk_bf16_f32 v31, v38, v40
	s_waitcnt lgkmcnt(2)
	v_cvt_pk_bf16_f32 v32, v42, v44
	s_waitcnt lgkmcnt(0)
	v_cvt_pk_bf16_f32 v33, v84, v86
	v_lshl_add_u64 v[90:91], v[88:89], 0, v[90:91]
	v_add_u32_e32 v34, s8, v48
	global_store_dwordx4 v[90:91], v[30:33], off nt
	s_nop 1
	v_cvt_pk_bf16_f32 v30, v37, v35
	v_ashrrev_i32_e32 v35, 31, v34
	v_cvt_pk_bf16_f32 v31, v39, v41
	v_cvt_pk_bf16_f32 v32, v43, v45
	v_cvt_pk_bf16_f32 v33, v85, v87
	v_lshlrev_b64 v[34:35], 11, v[34:35]
	ds_read2_b32 v[36:37], v83 offset0:49 offset1:57
	ds_read2_b32 v[38:39], v83 offset0:16 offset1:24
	ds_read2_b32 v[40:41], v83 offset0:82 offset1:90
	ds_read2_b32 v[42:43], v83 offset0:115 offset1:123
	ds_read2_b32 v[44:45], v83 offset0:148 offset1:156
	ds_read2_b32 v[84:85], v83 offset0:181 offset1:189
	ds_read2_b32 v[86:87], v83 offset0:214 offset1:222
	ds_read2_b32 v[90:91], v83 offset0:247 offset1:255
	v_lshl_add_u64 v[34:35], v[88:89], 0, v[34:35]
	global_store_dwordx4 v[34:35], v[30:33], off nt
	v_add_u32_e32 v34, s8, v49
	v_ashrrev_i32_e32 v35, 31, v34
	v_lshlrev_b64 v[34:35], 11, v[34:35]
	s_waitcnt lgkmcnt(6)
	v_cvt_pk_bf16_f32 v30, v38, v36
	s_waitcnt lgkmcnt(4)
	v_cvt_pk_bf16_f32 v31, v40, v42
	s_waitcnt lgkmcnt(2)
	v_cvt_pk_bf16_f32 v32, v44, v84
	s_waitcnt lgkmcnt(0)
	v_cvt_pk_bf16_f32 v33, v86, v90
	v_lshl_add_u64 v[34:35], v[88:89], 0, v[34:35]
	global_store_dwordx4 v[34:35], v[30:33], off nt
	v_add_u32_e32 v34, s8, v50
	v_ashrrev_i32_e32 v35, 31, v34
	v_lshlrev_b64 v[34:35], 11, v[34:35]
	v_cvt_pk_bf16_f32 v30, v39, v37
	v_cvt_pk_bf16_f32 v31, v41, v43
	v_cvt_pk_bf16_f32 v32, v45, v85
	v_cvt_pk_bf16_f32 v33, v87, v91
	v_lshl_add_u64 v[34:35], v[88:89], 0, v[34:35]
	global_store_dwordx4 v[34:35], v[30:33], off nt
	s_waitcnt lgkmcnt(0)

; #define LAS __attribute__((address_space(3)))
; DI unsigned pk2(float lo, float hi) { f32x2_t v = {lo, hi}; bf16x2_t b = __builtin_convertvector(v, bf16x2_t); return __builtin_bit_cast(unsigned, b); }
; DI void transpose_item(const float* W, int K, int N, bf16* WT, int k0, int n0, int drow0, LAS float* scr, int lane) {
; #pragma unroll 8
;     for (int i = 0; i < 32; ++i) { const int kk = 2 * i + (lane >> 5); scr[kk * 33 + (lane & 31)] = __builtin_nontemporal_load(W + (size_t)(k0 + kk) * N + n0 + (lane & 31)); }
;     asm volatile("s_waitcnt lgkmcnt(0)" ::: "memory");
;     const int c = lane & 7;
; #pragma unroll
;     for (int j = 0; j < 4; ++j) { const int n = (lane >> 3) + 8 * j; const LAS float* s = scr + (8 * c) * 33 + n;
;         u32x4 o; o.x = pk2(s[0 * 33], s[1 * 33]); o.y = pk2(s[2 * 33], s[3 * 33]); o.z = pk2(s[4 * 33], s[5 * 33]); o.w = pk2(s[6 * 33], s[7 * 33]);
;         *(u32x4*)(WT + (size_t)(drow0 + n) * K + k0 + 8 * c) = o; }
;     asm volatile("s_waitcnt lgkmcnt(0)" ::: "memory");
; __global__ void __launch_bounds__(512, 2) fwd_mega(Args args) {
;     ...
;             if (r < I_PA) { const int kb = r / 64, nb = r % 64; transpose_item(w_pa, 1024, DM, Wpat, 64 * kb, 32 * nb, 32 * nb, scr, lane); continue; } r -= I_PA;
.LBB0_41:
	v_lshl_add_u64 v[84:85], v[44:45], 0, s[8:9]
	v_lshl_add_u64 v[86:87], v[42:43], 0, s[8:9]
	v_lshl_add_u64 v[88:89], v[40:41], 0, s[8:9]
	v_lshl_add_u64 v[90:91], v[38:39], 0, s[8:9]
	v_lshl_add_u64 v[92:93], v[36:37], 0, s[8:9]
	v_lshl_add_u64 v[94:95], v[34:35], 0, s[8:9]
	v_lshl_add_u64 v[96:97], v[32:33], 0, s[8:9]
	v_lshl_add_u64 v[98:99], v[30:31], 0, s[8:9]
	global_load_dword v84, v[84:85], off nt
	s_nop 0
	global_load_dword v85, v[86:87], off nt
	s_nop 0
	global_load_dword v86, v[88:89], off nt
	global_load_dword v87, v[90:91], off nt
	s_nop 0
	global_load_dword v88, v[92:93], off nt
	global_load_dword v89, v[94:95], off nt
	global_load_dword v90, v[96:97], off nt
	global_load_dword v91, v[98:99], off nt
	s_add_u32 s8, s8, 0x20000
	s_addc_u32 s9, s9, 0
	v_add_u32_e32 v92, 0x400, v83
	s_cmp_lg_u32 s8, 0x80000
	s_waitcnt vmcnt(6)
	ds_write2_b32 v83, v84, v85 offset1:66
	s_waitcnt vmcnt(4)
	ds_write2_b32 v83, v86, v87 offset0:132 offset1:198
	s_waitcnt vmcnt(2)
	ds_write2_b32 v92, v88, v89 offset0:8 offset1:74
	s_waitcnt vmcnt(0)
	ds_write2_b32 v92, v90, v91 offset0:140 offset1:206
	v_add_u32_e32 v83, 0x840, v83
	s_cbranch_scc1 .LBB0_41
	s_waitcnt lgkmcnt(0)
	v_add_u32_e32 v83, 0x1000, v47
	s_lshl_b32 s8, s18, 5
	ds_read2_b32 v[34:35], v83 offset0:33 offset1:41
	ds_read2_b32 v[36:37], v83 offset1:8
	ds_read2_b32 v[38:39], v83 offset0:66 offset1:74
	ds_read2_b32 v[40:41], v83 offset0:99 offset1:107
	ds_read2_b32 v[42:43], v83 offset0:132 offset1:140
	ds_read2_b32 v[44:45], v83 offset0:165 offset1:173
	ds_read2_b32 v[84:85], v83 offset0:198 offset1:206
	ds_read2_b32 v[86:87], v83 offset0:231 offset1:239
	s_and_b32 s8, s8, 0x7e0
	v_add_u32_e32 v90, s8, v46
	s_add_i32 s0, s19, 0xffffd000
	v_ashrrev_i32_e32 v91, 31, v90
	v_lshl_add_u64 v[88:89], s[0:1], 1, v[14:15]
	v_lshlrev_b64 v[90:91], 11, v[90:91]
	s_waitcnt lgkmcnt(6)
	v_cvt_pk_bf16_f32 v30, v36, v34
	s_waitcnt lgkmcnt(4)
	v_cvt_pk_bf16_f32 v31, v38, v40
	s_waitcnt lgkmcnt(2)
	v_cvt_pk_bf16_f32 v32, v42, v44
	s_waitcnt lgkmcnt(0)
	v_cvt_pk_bf16_f32 v33, v84, v86
	v_lshl_add_u64 v[90:91], v[88:89], 0, v[90:91]
	v_add_u32_e32 v34, s8, v48
	global_store_dwordx4 v[90:91], v[30:33], off nt
	s_nop 1
	v_cvt_pk_bf16_f32 v30, v37, v35
	v_ashrrev_i32_e32 v35, 31, v34
	v_cvt_pk_bf16_f32 v31, v39, v41
	v_cvt_pk_bf16_f32 v32, v43, v45
	v_cvt_pk_bf16_f32 v33, v85, v87
	v_lshlrev_b64 v[34:35], 11, v[34:35]
	ds_read2_b32 v[36:37], v83 offset0:49 offset1:57
	ds_read2_b32 v[38:39], v83 offset0:16 offset1:24
	ds_read2_b32 v[40:41], v83 offset0:82 offset1:90
	ds_read2_b32 v[42:43], v83 offset0:115 offset1:123
	ds_read2_b32 v[44:45], v83 offset0:148 offset1:156
	ds_read2_b32 v[84:85], v83 offset0:181 offset1:189
	ds_read2_b32 v[86:87], v83 offset0:214 offset1:222
	ds_read2_b32 v[90:91], v83 offset0:247 offset1:255
	v_lshl_add_u64 v[34:35], v[88:89], 0, v[34:35]
	global_store_dwordx4 v[34:35], v[30:33], off nt
	v_add_u32_e32 v34, s8, v49
	v_ashrrev_i32_e32 v35, 31, v34
	v_lshlrev_b64 v[34:35], 11, v[34:35]
	s_waitcnt lgkmcnt(6)
	v_cvt_pk_bf16_f32 v30, v38, v36
	s_waitcnt lgkmcnt(4)
	v_cvt_pk_bf16_f32 v31, v40, v42
	s_waitcnt lgkmcnt(2)
	v_cvt_pk_bf16_f32 v32, v44, v84
	s_waitcnt lgkmcnt(0)
	v_cvt_pk_bf16_f32 v33, v86, v90
	v_lshl_add_u64 v[34:35], v[88:89], 0, v[34:35]
	global_store_dwordx4 v[34:35], v[30:33], off nt
	v_add_u32_e32 v34, s8, v50
	v_ashrrev_i32_e32 v35, 31, v34
	v_lshlrev_b64 v[34:35], 11, v[34:35]
	v_cvt_pk_bf16_f32 v30, v39, v37
	v_cvt_pk_bf16_f32 v31, v41, v43
	v_cvt_pk_bf16_f32 v32, v45, v85
	v_cvt_pk_bf16_f32 v33, v87, v91
	v_lshl_add_u64 v[34:35], v[88:89], 0, v[34:35]
	global_store_dwordx4 v[34:35], v[30:33], off nt
	s_waitcnt lgkmcnt(0)

; #define LAS __attribute__((address_space(3)))
; DI unsigned pk2(float lo, float hi) { f32x2_t v = {lo, hi}; bf16x2_t b = __builtin_convertvector(v, bf16x2_t); return __builtin_bit_cast(unsigned, b); }
; DI void transpose_item(const float* W, int K, int N, bf16* WT, int k0, int n0, int drow0, LAS float* scr, int lane) {
; #pragma unroll 8
;     for (int i = 0; i < 32; ++i) { const int kk = 2 * i + (lane >> 5); scr[kk * 33 + (lane & 31)] = __builtin_nontemporal_load(W + (size_t)(k0 + kk) * N + n0 + (lane & 31)); }
;     asm volatile("s_waitcnt lgkmcnt(0)" ::: "memory");
;     const int c = lane & 7;
; #pragma unroll
;     for (int j = 0; j < 4; ++j) { const int n = (lane >> 3) + 8 * j; const LAS float* s = scr + (8 * c) * 33 + n;
;         u32x4 o; o.x = pk2(s[0 * 33], s[1 * 33]); o.y = pk2(s[2 * 33], s[3 * 33]); o.z = pk2(s[4 * 33], s[5 * 33]); o.w = pk2(s[6 * 33], s[7 * 33]);
;         *(u32x4*)(WT + (size_t)(drow0 + n) * K + k0 + 8 * c) = o; }
;     asm volatile("s_waitcnt lgkmcnt(0)" ::: "memory");
; __global__ void __launch_bounds__(512, 2) fwd_mega(Args args) {
;     ...
;             if (r < I_IN) { const int kb = r / 384, nb = r % 384, n0 = 32 * nb; transpose_item(w_in, DM, NIN, Wint, 64 * kb, n0, kInRowMap[n0 >> 10] + (n0 & 1023), scr, lane); continue; } r -= I_IN;
.LBB0_46:
	v_lshl_add_u64 v[84:85], v[44:45], 0, s[24:25]
	v_lshl_add_u64 v[86:87], v[42:43], 0, s[24:25]
	v_lshl_add_u64 v[88:89], v[40:41], 0, s[24:25]
	v_lshl_add_u64 v[90:91], v[38:39], 0, s[24:25]
	v_lshl_add_u64 v[92:93], v[36:37], 0, s[24:25]
	v_lshl_add_u64 v[94:95], v[34:35], 0, s[24:25]
	v_lshl_add_u64 v[96:97], v[32:33], 0, s[24:25]
	v_lshl_add_u64 v[98:99], v[30:31], 0, s[24:25]
	global_load_dword v84, v[84:85], off nt
	s_nop 0
	global_load_dword v85, v[86:87], off nt
	s_nop 0
	global_load_dword v86, v[88:89], off nt
	global_load_dword v87, v[90:91], off nt
	s_nop 0
	global_load_dword v88, v[92:93], off nt
	global_load_dword v89, v[94:95], off nt
	global_load_dword v90, v[96:97], off nt
	global_load_dword v91, v[98:99], off nt
	s_add_u32 s24, s24, 0xc0000
	s_addc_u32 s25, s25, 0
	v_add_u32_e32 v92, 0x400, v83
	s_cmp_lg_u32 s24, 0x300000
	s_waitcnt vmcnt(6)
	ds_write2_b32 v83, v84, v85 offset1:66
	s_waitcnt vmcnt(4)
	ds_write2_b32 v83, v86, v87 offset0:132 offset1:198
	s_waitcnt vmcnt(2)
	ds_write2_b32 v92, v88, v89 offset0:8 offset1:74
	s_waitcnt vmcnt(0)
	ds_write2_b32 v92, v90, v91 offset0:140 offset1:206
	v_add_u32_e32 v83, 0x840, v83
	s_cbranch_scc1 .LBB0_46
	s_waitcnt lgkmcnt(0)
	v_add_u32_e32 v83, 0x1000, v47
	s_and_b32 s19, s22, 0x3e0
	ds_read2_b32 v[34:35], v83 offset0:33 offset1:41
	ds_read2_b32 v[36:37], v83 offset1:8
	ds_read2_b32 v[38:39], v83 offset0:66 offset1:74
	ds_read2_b32 v[40:41], v83 offset0:99 offset1:107
	ds_read2_b32 v[42:43], v83 offset0:132 offset1:140
	ds_read2_b32 v[44:45], v83 offset0:165 offset1:173
	ds_read2_b32 v[84:85], v83 offset0:198 offset1:206
	ds_read2_b32 v[86:87], v83 offset0:231 offset1:239
	s_waitcnt lgkmcnt(0)
	s_add_i32 s0, s0, s19
	v_add_u32_e32 v90, s0, v46
	v_ashrrev_i32_e32 v91, 31, v90
	v_lshl_add_u64 v[88:89], s[8:9], 1, v[16:17]
	v_lshlrev_b64 v[90:91], 12, v[90:91]
	v_cvt_pk_bf16_f32 v30, v36, v34
	v_cvt_pk_bf16_f32 v31, v38, v40
	v_cvt_pk_bf16_f32 v32, v42, v44
	v_cvt_pk_bf16_f32 v33, v84, v86
	v_lshl_add_u64 v[90:91], v[88:89], 0, v[90:91]
	v_add_u32_e32 v34, s0, v48
	global_store_dwordx4 v[90:91], v[30:33], off nt
	s_nop 1
	v_cvt_pk_bf16_f32 v30, v37, v35
	v_ashrrev_i32_e32 v35, 31, v34
	v_cvt_pk_bf16_f32 v31, v39, v41
	v_cvt_pk_bf16_f32 v32, v43, v45
	v_cvt_pk_bf16_f32 v33, v85, v87
	v_lshlrev_b64 v[34:35], 12, v[34:35]
	ds_read2_b32 v[36:37], v83 offset0:49 offset1:57
	ds_read2_b32 v[38:39], v83 offset0:16 offset1:24
	ds_read2_b32 v[40:41], v83 offset0:82 offset1:90
	ds_read2_b32 v[42:43], v83 offset0:115 offset1:123
	ds_read2_b32 v[44:45], v83 offset0:148 offset1:156
	ds_read2_b32 v[84:85], v83 offset0:181 offset1:189
	ds_read2_b32 v[86:87], v83 offset0:214 offset1:222
	ds_read2_b32 v[90:91], v83 offset0:247 offset1:255
	v_lshl_add_u64 v[34:35], v[88:89], 0, v[34:35]
	global_store_dwordx4 v[34:35], v[30:33], off nt
	v_add_u32_e32 v34, s0, v49
	v_ashrrev_i32_e32 v35, 31, v34
	v_lshlrev_b64 v[34:35], 12, v[34:35]
	s_waitcnt lgkmcnt(6)
	v_cvt_pk_bf16_f32 v30, v38, v36
	s_waitcnt lgkmcnt(4)
	v_cvt_pk_bf16_f32 v31, v40, v42
	s_waitcnt lgkmcnt(2)
	v_cvt_pk_bf16_f32 v32, v44, v84
	s_waitcnt lgkmcnt(0)
	v_cvt_pk_bf16_f32 v33, v86, v90
	v_lshl_add_u64 v[34:35], v[88:89], 0, v[34:35]
	global_store_dwordx4 v[34:35], v[30:33], off nt
	v_add_u32_e32 v34, s0, v50
	v_ashrrev_i32_e32 v35, 31, v34
	v_lshlrev_b64 v[34:35], 12, v[34:35]
	v_cvt_pk_bf16_f32 v30, v39, v37
	v_cvt_pk_bf16_f32 v31, v41, v43
	v_cvt_pk_bf16_f32 v32, v45, v85
	v_cvt_pk_bf16_f32 v33, v87, v91
	v_lshl_add_u64 v[34:35], v[88:89], 0, v[34:35]
	global_store_dwordx4 v[34:35], v[30:33], off nt
	s_waitcnt lgkmcnt(0)
	s_branch .LBB0_15
